# v38: v36 + prologue XN / rstd stores write-through (sc1) so the grid barrier's L2 write-back after the prologue finds little left to flush
# speedup vs baseline: 1.0057x; 1.0057x over previous
; __device__ __forceinline__ unsigned cvt_pk_bf16(float lo, float hi) { unsigned r; asm volatile("v_cvt_pk_bf16_f32 %0, %1, %2" : "=v"(r) : "v"(lo), "v"(hi)); return r; }
; __device__ __forceinline__ void xrow_finish(const XRow& r, bf16* __restrict__ orow, float* __restrict__ rsp, int lane) {
;     float s = 0.f;
; #pragma unroll
;     for (int j = 0; j < 4; ++j) s += (r.v[j].x * r.v[j].x + r.v[j].y * r.v[j].y) + (r.v[j].z * r.v[j].z + r.v[j].w * r.v[j].w);
;     const float rstd = rsqrtf(wave_sum(s) * (1.f / DM) + EPS);
;     if (lane == 0) *rsp = rstd;
;     v2u* o8 = (v2u*)orow + lane;
; #pragma unroll
;     for (int j = 0; j < 4; ++j) { v2u o; o.x = pg8::cvt_pk_bf16(r.v[j].x, r.v[j].y); o.y = pg8::cvt_pk_bf16(r.v[j].z, r.v[j].w); o8[64 * j] = o; }
; __global__ void __launch_bounds__(NWAVES * 64, 2) hybrid_fwd(Args args) {
;     ...
;               if (nk > 0) { XRow x0, x1, x2;
;                 { const int ma = PR_ROW(0); xrow_load(x0, X_SRC(ma), lane); }
;                 { const int kb = 1 < nk ? 1 : 0; const int mb = PR_ROW(kb); xrow_load(x1, X_SRC(mb), lane); }
; #pragma unroll 1
;                 for (int k = 0; k < nk; ++k) {
;                     { const int kc = k + 2 < nk ? k + 2 : k; const int mc = PR_ROW(kc); xrow_load(x2, X_SRC(mc), lane); }
;                     const int m = PR_ROW(k);
;                     xrow_finish(x0, (bf16*)args.out + (size_t)m * 2 * DM, (float*)(ws + WS_RS) + m, lane);
;                     x0 = x1; x1 = x2;
;                 } }
.LBB0_634:
	s_or_b64 exec, exec, s[4:5]
	s_lshl_b64 s[4:5], s[0:1], 12
	v_lshl_add_u64 v[52:53], v[48:49], 0, s[4:5]
	v_cvt_pk_bf16_f32 v28, v28, v29
	v_cvt_pk_bf16_f32 v29, v30, v31
	global_store_dwordx2 v[52:53], v[28:29], off sc1
	v_cvt_pk_bf16_f32 v20, v20, v21
	v_cvt_pk_bf16_f32 v21, v22, v23
	global_store_dwordx2 v[52:53], v[20:21], off offset:512 sc1
	v_cvt_pk_bf16_f32 v4, v4, v5
	v_cvt_pk_bf16_f32 v5, v6, v7
	global_store_dwordx2 v[52:53], v[4:5], off offset:1024 sc1
	v_cvt_pk_bf16_f32 v0, v0, v1
	v_cvt_pk_bf16_f32 v1, v2, v3
	global_store_dwordx2 v[52:53], v[0:1], off offset:1536 sc1
	s_waitcnt vmcnt(11)
	v_mov_b64_e32 v[0:1], v[8:9]
	s_waitcnt vmcnt(10)
	v_mov_b64_e32 v[4:5], v[12:13]
	s_waitcnt vmcnt(9)
	v_mov_b64_e32 v[22:23], v[18:19]
	s_waitcnt vmcnt(8)
	v_mov_b64_e32 v[30:31], v[26:27]
	s_add_i32 s8, s8, 1
	s_add_i32 s0, s0, s93
	v_mov_b64_e32 v[2:3], v[10:11]
	v_mov_b64_e32 v[6:7], v[14:15]
	v_mov_b64_e32 v[20:21], v[16:17]
	v_mov_b64_e32 v[28:29], v[24:25]
	s_waitcnt vmcnt(4)
	v_mov_b64_e32 v[8:9], v[44:45]
	v_mov_b64_e32 v[12:13], v[40:41]
	v_mov_b64_e32 v[16:17], v[36:37]
	v_mov_b64_e32 v[24:25], v[32:33]
	s_cmp_lg_u32 s2, s8
	v_mov_b64_e32 v[10:11], v[46:47]
	v_mov_b64_e32 v[14:15], v[42:43]
	v_mov_b64_e32 v[18:19], v[38:39]
	v_mov_b64_e32 v[26:27], v[34:35]
	s_cbranch_scc0 .LBB0_637
.LBB0_635:
	s_add_i32 s1, s8, 2
	s_cmp_lt_i32 s1, s2
	s_cselect_b32 s1, s1, s8
	s_mul_i32 s1, s1, s93
	s_add_i32 s1, s1, s92
	s_add_i32 s4, s1, 0xffffc000
	s_ashr_i32 s5, s1, 31
	s_cmpk_lt_i32 s1, 0x4000
	v_readlane_b32 s12, v254, 31
	s_cselect_b32 s5, s5, 0
	s_cselect_b32 s4, s1, s4
	v_readlane_b32 s13, v254, 32
	v_readlane_b32 s14, v254, 33
	v_readlane_b32 s15, v254, 34
	s_cselect_b32 s1, s13, s15
	s_cselect_b32 s6, s12, s14
	s_lshl_b64 s[4:5], s[4:5], 12
	s_add_u32 s4, s6, s4
	s_addc_u32 s5, s1, s5
	global_load_dwordx4 v[32:35], v50, s[4:5] nt
	global_load_dwordx4 v[36:39], v50, s[4:5] offset:1024 nt
	global_load_dwordx4 v[40:43], v50, s[4:5] offset:2048 nt
	global_load_dwordx4 v[44:47], v50, s[4:5] offset:3072 nt
	s_waitcnt vmcnt(11)
	v_mul_f32_e32 v51, v29, v29
	v_mul_f32_e32 v52, v31, v31
	v_fmac_f32_e32 v51, v28, v28
	v_fmac_f32_e32 v52, v30, v30
	v_add_f32_e32 v51, v51, v52
	s_waitcnt vmcnt(10)
	v_mul_f32_e32 v52, v21, v21
	v_mul_f32_e32 v53, v23, v23
	v_fmac_f32_e32 v52, v20, v20
	v_fmac_f32_e32 v53, v22, v22
	v_add_f32_e32 v52, v52, v53
	v_add_f32_e32 v51, v51, v52
	s_waitcnt vmcnt(9)
	v_mul_f32_e32 v52, v5, v5
	v_mul_f32_e32 v53, v7, v7
	v_fmac_f32_e32 v52, v4, v4
	v_fmac_f32_e32 v53, v6, v6
	v_add_f32_e32 v52, v52, v53
	v_add_f32_e32 v51, v51, v52
	s_waitcnt vmcnt(8)
	v_mul_f32_e32 v52, v1, v1
	v_mul_f32_e32 v53, v3, v3
	v_fmac_f32_e32 v52, v0, v0
	v_fmac_f32_e32 v53, v2, v2
	v_add_f32_e32 v52, v52, v53
	v_add_f32_e32 v51, v51, v52
	v_mov_b32_e32 v52, v129
	s_ashr_i32 s1, s0, 31
	v_add_f32_dpp v51, v51, v51 quad_perm:[1,0,3,2] row_mask:0xf bank_mask:0xf bound_ctrl:1
	v_readlane_b32 s16, v254, 35
	v_readlane_b32 s17, v254, 36
	v_add_f32_dpp v51, v51, v51 quad_perm:[2,3,0,1] row_mask:0xf bank_mask:0xf bound_ctrl:1
	v_readlane_b32 s18, v254, 37
	v_readlane_b32 s19, v254, 38
	v_add_f32_dpp v51, v51, v51 row_half_mirror row_mask:0xf bank_mask:0xf bound_ctrl:1
	s_nop 1
	v_add_f32_dpp v51, v51, v51 row_mirror row_mask:0xf bank_mask:0xf bound_ctrl:1
	s_nop 1
	v_mov_b32_dpp v52, v51 row_bcast:15 row_mask:0xa bank_mask:0xf
	v_add_f32_e32 v51, v51, v52
	v_mov_b32_e32 v52, v129
	s_nop 1
	v_mov_b32_dpp v52, v51 row_bcast:31 row_mask:0xc bank_mask:0xf
	v_add_f32_e32 v51, v51, v52
	s_nop 0
	v_readlane_b32 s6, v51, 63
	s_and_saveexec_b64 s[4:5], vcc
	s_cbranch_execz .LBB0_634
	v_fma_f32 v51, s6, v183, v168
	v_mul_f32_e32 v52, 0x4b800000, v51
	v_cmp_gt_f32_e64 s[6:7], s79, v51
	s_lshl_b64 s[10:11], s[0:1], 2
	s_add_u32 s10, s82, s10
	v_cndmask_b32_e64 v51, v51, v52, s[6:7]
	v_rsq_f32_e32 v51, v51
	s_addc_u32 s11, s83, s11
	v_mul_f32_e32 v52, 0x45800000, v51
	v_cndmask_b32_e64 v51, v51, v52, s[6:7]
	global_store_dword v129, v51, s[10:11] sc1
	s_branch .LBB0_634
